# meta-row unit epilogue stores (residual and GU GEMMs) device-scope
# speedup vs baseline: 1.0019x; 1.0016x over previous
; template <class Epi, class Pre>
; __device__ __forceinline__ void meta_gemm(const bf16_t* __restrict__ A, int lda, const bf16_t* __restrict__ Bt, int ldb, int N, int K, Epi& epi, Pre pre) {
;     ...
;   for (int u = blockIdx.x; u < nunits; u += gridDim.x) {
;     const int cb = (u >> 2) * 256 + (u & 3) * 32;
;     f32x4 acc[2][2];
; #pragma unroll
;     for (int bj = 0; bj < 2; ++bj)
; #pragma unroll
;       for (int n = 0; n < 2; ++n) acc[bj][n] = (f32x4){0.f, 0.f, 0.f, 0.f};
;     const bf16_t* ap = A + (size_t)(NREAL + fr) * lda + wid * ks + fq * 8;
;     const bf16_t* bp = Bt + (size_t)(cb + fr) * ldb + wid * ks + fq * 8;
; #pragma unroll 4
;     for (int k0 = 0; k0 < ks; k0 += 32) {
;       const bf16x8 a = *(const bf16x8*)(ap + k0);
; #pragma unroll
;       for (int bj = 0; bj < 2; ++bj)
; #pragma unroll
;         for (int n = 0; n < 2; ++n) { const bf16x8 b = *(const bf16x8*)(bp + (size_t)(bj * 128 + n * 16) * ldb + k0); acc[bj][n] = __builtin_amdgcn_mfma_f32_16x16x32_bf16(b, a, acc[bj][n], 0, 0, 0); }
;     }
; #pragma unroll
;     for (int bj = 0; bj < 2; ++bj)
; #pragma unroll
;       for (int n = 0; n < 2; ++n)
; #pragma unroll
;         for (int j = 0; j < 4; ++j) part[(wid * 16 + (bj * 2 + n) * 4 + j) * 64 + lane] = acc[bj][n][j];
;     __syncthreads();
;     if (wid < 4) {
;       f32x4 v[2][2];
; #pragma unroll
;       for (int bj = 0; bj < 2; ++bj)
; #pragma unroll
;         for (int n = 0; n < 2; ++n)
; #pragma unroll
;           for (int j = 0; j < 4; ++j) { float s = 0.f;
; #pragma unroll
;             for (int w = 0; w < 8; ++w) s += part[(w * 16 + (bj * 2 + n) * 4 + j) * 64 + lane];
;             v[bj][n][j] = s; }
.LBB0_1446:
	s_and_b32 s10, s1, 0x60
	s_and_b32 s11, s0, 0xffffff00
	s_or_b32 s12, s11, s10
	v_or_b32_e32 v2, s12, v0
	v_ashrrev_i32_e32 v3, 31, v2
	v_lshlrev_b64 v[2:3], 11, v[2:3]
	v_lshl_add_u64 v[32:33], v[20:21], 0, v[2:3]
	s_mov_b32 s10, 0x8000
	v_add_co_u32_e32 v34, vcc, s10, v32
	s_mov_b32 s10, 0x40000
	s_nop 0
	v_addc_co_u32_e32 v35, vcc, 0, v33, vcc
	v_add_co_u32_e32 v36, vcc, s10, v32
	s_mov_b32 s10, 0x48000
	s_nop 0
	v_addc_co_u32_e32 v37, vcc, 0, v33, vcc
	v_add_co_u32_e32 v38, vcc, s10, v32
	global_load_dwordx4 v[2:5], v[18:19], off
	global_load_dwordx4 v[6:9], v[32:33], off
	v_addc_co_u32_e32 v39, vcc, 0, v33, vcc
	global_load_dwordx4 v[10:13], v[34:35], off
	global_load_dwordx4 v[14:17], v[36:37], off
	global_load_dwordx4 v[24:27], v[38:39], off
	global_load_dwordx4 v[54:57], v[18:19], off offset:64
	global_load_dwordx4 v[58:61], v[32:33], off offset:64
	global_load_dwordx4 v[62:65], v[34:35], off offset:64
	global_load_dwordx4 v[66:69], v[36:37], off offset:64
	global_load_dwordx4 v[70:73], v[38:39], off offset:64
	global_load_dwordx4 v[74:77], v[18:19], off offset:128
	global_load_dwordx4 v[78:81], v[32:33], off offset:128
	global_load_dwordx4 v[82:85], v[34:35], off offset:128
	global_load_dwordx4 v[86:89], v[36:37], off offset:128
	global_load_dwordx4 v[90:93], v[38:39], off offset:128
	global_load_dwordx4 v[94:97], v[18:19], off offset:192
	global_load_dwordx4 v[98:101], v[32:33], off offset:192
	global_load_dwordx4 v[102:105], v[34:35], off offset:192
	global_load_dwordx4 v[106:109], v[36:37], off offset:192
	global_load_dwordx4 v[110:113], v[38:39], off offset:192
	s_waitcnt vmcnt(18)
	v_mfma_f32_16x16x32_bf16 v[6:9], v[6:9], v[2:5], 0
	s_waitcnt vmcnt(17)
	v_mfma_f32_16x16x32_bf16 v[10:13], v[10:13], v[2:5], 0
	s_waitcnt vmcnt(16)
	v_mfma_f32_16x16x32_bf16 v[14:17], v[14:17], v[2:5], 0
	s_waitcnt vmcnt(15)
	v_mfma_f32_16x16x32_bf16 v[2:5], v[24:27], v[2:5], 0
	s_waitcnt vmcnt(13)
	v_mfma_f32_16x16x32_bf16 v[6:9], v[58:61], v[54:57], v[6:9]
	s_waitcnt vmcnt(12)
	v_mfma_f32_16x16x32_bf16 v[10:13], v[62:65], v[54:57], v[10:13]
	s_waitcnt vmcnt(11)
	v_mfma_f32_16x16x32_bf16 v[14:17], v[66:69], v[54:57], v[14:17]
	s_waitcnt vmcnt(10)
	v_mfma_f32_16x16x32_bf16 v[2:5], v[70:73], v[54:57], v[2:5]
	s_waitcnt vmcnt(8)
	v_mfma_f32_16x16x32_bf16 v[6:9], v[78:81], v[74:77], v[6:9]
	s_waitcnt vmcnt(7)
	v_mfma_f32_16x16x32_bf16 v[10:13], v[82:85], v[74:77], v[10:13]
	s_waitcnt vmcnt(6)
	v_mfma_f32_16x16x32_bf16 v[14:17], v[86:89], v[74:77], v[14:17]
	s_waitcnt vmcnt(5)
	v_mfma_f32_16x16x32_bf16 v[2:5], v[90:93], v[74:77], v[2:5]
	s_waitcnt vmcnt(3)
	v_mfma_f32_16x16x32_bf16 v[6:9], v[98:101], v[94:97], v[6:9]
	s_waitcnt vmcnt(2)
	v_mfma_f32_16x16x32_bf16 v[10:13], v[102:105], v[94:97], v[10:13]
	s_waitcnt vmcnt(1)
	v_mfma_f32_16x16x32_bf16 v[14:17], v[106:109], v[94:97], v[14:17]
	s_waitcnt vmcnt(0)
	v_mfma_f32_16x16x32_bf16 v[2:5], v[110:113], v[94:97], v[2:5]
	s_nop 3
	ds_write2st64_b32 v43, v6, v7 offset1:1
	ds_write2st64_b32 v43, v8, v9 offset0:2 offset1:3
	ds_write2st64_b32 v43, v10, v11 offset0:4 offset1:5
	ds_write2st64_b32 v43, v12, v13 offset0:6 offset1:7
	s_nop 0
	ds_write2st64_b32 v43, v14, v15 offset0:8 offset1:9
	ds_write2st64_b32 v43, v16, v17 offset0:10 offset1:11
	s_nop 0
	ds_write2st64_b32 v43, v2, v3 offset0:12 offset1:13
	ds_write2st64_b32 v43, v4, v5 offset0:14 offset1:15
	s_waitcnt lgkmcnt(0)
	s_barrier
	s_and_saveexec_b64 s[10:11], s[4:5]
	s_cbranch_execz .LBB0_1445
	ds_read2st64_b32 v[2:3], v42 offset1:1
	ds_read2st64_b32 v[4:5], v42 offset0:16 offset1:17
	ds_read2st64_b32 v[6:7], v42 offset0:32 offset1:33
	ds_read2st64_b32 v[8:9], v42 offset0:48 offset1:49
	ds_read2st64_b32 v[10:11], v42 offset0:64 offset1:65
	ds_read2st64_b32 v[12:13], v42 offset0:80 offset1:81
	ds_read2st64_b32 v[14:15], v42 offset0:96 offset1:97
	ds_read2st64_b32 v[16:17], v42 offset0:112 offset1:113
	ds_read2st64_b32 v[24:25], v42 offset0:2 offset1:3
	ds_read2st64_b32 v[26:27], v42 offset0:18 offset1:19
	ds_read2st64_b32 v[28:29], v42 offset0:34 offset1:35
	ds_read2st64_b32 v[30:31], v42 offset0:50 offset1:51
	ds_read2st64_b32 v[32:33], v42 offset0:66 offset1:67
	ds_read2st64_b32 v[34:35], v42 offset0:82 offset1:83
	ds_read2st64_b32 v[36:37], v42 offset0:98 offset1:99
	ds_read2st64_b32 v[38:39], v42 offset0:114 offset1:115
	s_waitcnt lgkmcnt(7)
	v_pk_add_f32 v[24:25], v[24:25], 0 op_sel_hi:[1,0]
	v_pk_add_f32 v[2:3], v[2:3], 0 op_sel_hi:[1,0]
	s_ashr_i32 s13, s12, 31
	v_pk_add_f32 v[2:3], v[2:3], v[4:5]
	s_waitcnt lgkmcnt(6)
	v_pk_add_f32 v[4:5], v[24:25], v[26:27]
	v_pk_add_f32 v[2:3], v[2:3], v[6:7]
	s_waitcnt lgkmcnt(5)
	v_pk_add_f32 v[4:5], v[4:5], v[28:29]
	v_pk_add_f32 v[2:3], v[2:3], v[8:9]
	s_waitcnt lgkmcnt(4)
	v_pk_add_f32 v[4:5], v[4:5], v[30:31]
	v_pk_add_f32 v[2:3], v[2:3], v[10:11]
	s_waitcnt lgkmcnt(3)
	v_pk_add_f32 v[4:5], v[4:5], v[32:33]
	v_pk_add_f32 v[2:3], v[2:3], v[12:13]
	s_waitcnt lgkmcnt(2)
	v_pk_add_f32 v[4:5], v[4:5], v[34:35]
	v_pk_add_f32 v[2:3], v[2:3], v[14:15]
	s_waitcnt lgkmcnt(1)
	v_pk_add_f32 v[4:5], v[4:5], v[36:37]
	v_pk_add_f32 v[24:25], v[2:3], v[16:17]
	s_waitcnt lgkmcnt(0)
	v_pk_add_f32 v[26:27], v[4:5], v[38:39]
	ds_read2st64_b32 v[2:3], v42 offset0:4 offset1:5
	ds_read2st64_b32 v[4:5], v42 offset0:20 offset1:21
	ds_read2st64_b32 v[6:7], v42 offset0:36 offset1:37
	ds_read2st64_b32 v[8:9], v42 offset0:52 offset1:53
	ds_read2st64_b32 v[10:11], v42 offset0:68 offset1:69
	ds_read2st64_b32 v[12:13], v42 offset0:84 offset1:85
	ds_read2st64_b32 v[14:15], v42 offset0:100 offset1:101
	ds_read2st64_b32 v[16:17], v42 offset0:116 offset1:117
	ds_read2st64_b32 v[28:29], v42 offset0:6 offset1:7
	ds_read2st64_b32 v[30:31], v42 offset0:22 offset1:23
	ds_read2st64_b32 v[32:33], v42 offset0:38 offset1:39
	ds_read2st64_b32 v[34:35], v42 offset0:54 offset1:55
	ds_read2st64_b32 v[36:37], v42 offset0:70 offset1:71
	ds_read2st64_b32 v[38:39], v42 offset0:86 offset1:87
	ds_read2st64_b32 v[40:41], v42 offset0:102 offset1:103
	ds_read2st64_b32 v[44:45], v42 offset0:118 offset1:119
	s_waitcnt lgkmcnt(7)
; template <class Epi, class Pre>
; __device__ __forceinline__ void meta_gemm(const bf16_t* __restrict__ A, int lda, const bf16_t* __restrict__ Bt, int ldb, int N, int K, Epi& epi, Pre pre) {
;     ...
;       for (int bj = 0; bj < 2; ++bj)
; #pragma unroll
;         for (int n = 0; n < 2; ++n)
; #pragma unroll
;           for (int j = 0; j < 4; ++j) { float s = 0.f;
; #pragma unroll
;             for (int w = 0; w < 8; ++w) s += part[(w * 16 + (bj * 2 + n) * 4 + j) * 64 + lane];
;             v[bj][n][j] = s; }
;       pre(fr, fq);
;       epi(NREAL + 16 * wid + fr, cb, fq, v[0][0], v[0][1], v[1][0], v[1][1]);
	v_pk_add_f32 v[28:29], v[28:29], 0 op_sel_hi:[1,0]
	v_pk_add_f32 v[2:3], v[2:3], 0 op_sel_hi:[1,0]
	s_nop 0
	v_pk_add_f32 v[2:3], v[2:3], v[4:5]
	s_waitcnt lgkmcnt(6)
	v_pk_add_f32 v[4:5], v[28:29], v[30:31]
	v_pk_add_f32 v[2:3], v[2:3], v[6:7]
	s_waitcnt lgkmcnt(5)
	v_pk_add_f32 v[4:5], v[4:5], v[32:33]
	v_pk_add_f32 v[2:3], v[2:3], v[8:9]
	s_waitcnt lgkmcnt(4)
	v_pk_add_f32 v[4:5], v[4:5], v[34:35]
	v_pk_add_f32 v[2:3], v[2:3], v[10:11]
	s_waitcnt lgkmcnt(3)
	v_pk_add_f32 v[4:5], v[4:5], v[36:37]
	v_pk_add_f32 v[2:3], v[2:3], v[12:13]
	s_waitcnt lgkmcnt(2)
	v_pk_add_f32 v[4:5], v[4:5], v[38:39]
	v_pk_add_f32 v[2:3], v[2:3], v[14:15]
	s_waitcnt lgkmcnt(1)
	v_pk_add_f32 v[4:5], v[4:5], v[40:41]
	v_pk_add_f32 v[28:29], v[2:3], v[16:17]
	s_waitcnt lgkmcnt(0)
	v_pk_add_f32 v[30:31], v[4:5], v[44:45]
	ds_read2st64_b32 v[2:3], v42 offset0:8 offset1:9
	ds_read2st64_b32 v[4:5], v42 offset0:24 offset1:25
	ds_read2st64_b32 v[6:7], v42 offset0:40 offset1:41
	ds_read2st64_b32 v[8:9], v42 offset0:56 offset1:57
	ds_read2st64_b32 v[10:11], v42 offset0:72 offset1:73
	ds_read2st64_b32 v[12:13], v42 offset0:88 offset1:89
	ds_read2st64_b32 v[14:15], v42 offset0:104 offset1:105
	ds_read2st64_b32 v[16:17], v42 offset0:120 offset1:121
	ds_read2st64_b32 v[32:33], v42 offset0:10 offset1:11
	ds_read2st64_b32 v[34:35], v42 offset0:26 offset1:27
	ds_read2st64_b32 v[36:37], v42 offset0:42 offset1:43
	ds_read2st64_b32 v[38:39], v42 offset0:58 offset1:59
	ds_read2st64_b32 v[40:41], v42 offset0:74 offset1:75
	ds_read2st64_b32 v[44:45], v42 offset0:90 offset1:91
	ds_read2st64_b32 v[46:47], v42 offset0:106 offset1:107
	ds_read2st64_b32 v[48:49], v42 offset0:122 offset1:123
	s_waitcnt lgkmcnt(7)
	v_pk_add_f32 v[32:33], v[32:33], 0 op_sel_hi:[1,0]
	v_pk_add_f32 v[2:3], v[2:3], 0 op_sel_hi:[1,0]
	s_nop 0
	v_pk_add_f32 v[2:3], v[2:3], v[4:5]
	s_waitcnt lgkmcnt(6)
	v_pk_add_f32 v[4:5], v[32:33], v[34:35]
	v_pk_add_f32 v[2:3], v[2:3], v[6:7]
	s_waitcnt lgkmcnt(5)
	v_pk_add_f32 v[4:5], v[4:5], v[36:37]
	v_pk_add_f32 v[2:3], v[2:3], v[8:9]
	s_waitcnt lgkmcnt(4)
	v_pk_add_f32 v[4:5], v[4:5], v[38:39]
	v_pk_add_f32 v[2:3], v[2:3], v[10:11]
	s_waitcnt lgkmcnt(3)
	v_pk_add_f32 v[4:5], v[4:5], v[40:41]
	v_pk_add_f32 v[2:3], v[2:3], v[12:13]
	s_waitcnt lgkmcnt(2)
	v_pk_add_f32 v[4:5], v[4:5], v[44:45]
	v_pk_add_f32 v[2:3], v[2:3], v[14:15]
	s_waitcnt lgkmcnt(1)
	v_pk_add_f32 v[4:5], v[4:5], v[46:47]
	v_pk_add_f32 v[32:33], v[2:3], v[16:17]
	s_waitcnt lgkmcnt(0)
	v_pk_add_f32 v[34:35], v[4:5], v[48:49]
	ds_read2st64_b32 v[2:3], v42 offset0:12 offset1:13
	ds_read2st64_b32 v[4:5], v42 offset0:28 offset1:29
	ds_read2st64_b32 v[6:7], v42 offset0:44 offset1:45
	ds_read2st64_b32 v[8:9], v42 offset0:60 offset1:61
	ds_read2st64_b32 v[10:11], v42 offset0:76 offset1:77
	ds_read2st64_b32 v[12:13], v42 offset0:92 offset1:93
	ds_read2st64_b32 v[14:15], v42 offset0:108 offset1:109
	ds_read2st64_b32 v[16:17], v42 offset0:124 offset1:125
	ds_read2st64_b32 v[36:37], v42 offset0:14 offset1:15
	ds_read2st64_b32 v[38:39], v42 offset0:30 offset1:31
	ds_read2st64_b32 v[40:41], v42 offset0:46 offset1:47
	ds_read2st64_b32 v[44:45], v42 offset0:62 offset1:63
	ds_read2st64_b32 v[46:47], v42 offset0:78 offset1:79
	ds_read2st64_b32 v[48:49], v42 offset0:94 offset1:95
	ds_read2st64_b32 v[50:51], v42 offset0:110 offset1:111
	ds_read2st64_b32 v[52:53], v42 offset0:126 offset1:127
	s_waitcnt lgkmcnt(7)
	v_pk_add_f32 v[36:37], v[36:37], 0 op_sel_hi:[1,0]
	v_pk_add_f32 v[2:3], v[2:3], 0 op_sel_hi:[1,0]
	s_nop 0
	v_pk_add_f32 v[2:3], v[2:3], v[4:5]
	s_waitcnt lgkmcnt(6)
	v_pk_add_f32 v[4:5], v[36:37], v[38:39]
	v_pk_add_f32 v[2:3], v[2:3], v[6:7]
	s_waitcnt lgkmcnt(5)
	v_pk_add_f32 v[4:5], v[4:5], v[40:41]
	v_pk_add_f32 v[2:3], v[2:3], v[8:9]
	s_waitcnt lgkmcnt(4)
	v_pk_add_f32 v[4:5], v[4:5], v[44:45]
	v_pk_add_f32 v[2:3], v[2:3], v[10:11]
	s_waitcnt lgkmcnt(3)
	v_pk_add_f32 v[4:5], v[4:5], v[46:47]
	v_pk_add_f32 v[2:3], v[2:3], v[12:13]
	s_waitcnt lgkmcnt(2)
	v_pk_add_f32 v[4:5], v[4:5], v[48:49]
	v_pk_add_f32 v[2:3], v[2:3], v[14:15]
	s_waitcnt lgkmcnt(1)
	v_pk_add_f32 v[4:5], v[4:5], v[50:51]
	v_lshl_add_u64 v[40:41], s[12:13], 2, v[22:23]
	v_pk_add_f32 v[36:37], v[2:3], v[16:17]
	s_waitcnt lgkmcnt(0)
	v_pk_add_f32 v[38:39], v[4:5], v[52:53]
	global_load_dwordx4 v[2:5], v[40:41], off
	global_load_dwordx4 v[6:9], v[40:41], off offset:64
	global_load_dwordx4 v[10:13], v[40:41], off offset:512
	global_load_dwordx4 v[14:17], v[40:41], off offset:576
	s_waitcnt vmcnt(3)
	v_pk_add_f32 v[4:5], v[26:27], v[4:5]
	v_pk_add_f32 v[2:3], v[24:25], v[2:3]
	global_store_dwordx4 v[40:41], v[2:5], off sc1
	s_waitcnt vmcnt(3)
	s_nop 0
	v_pk_add_f32 v[4:5], v[30:31], v[8:9]
	v_pk_add_f32 v[2:3], v[28:29], v[6:7]
	global_store_dwordx4 v[40:41], v[2:5], off offset:64 sc1
	s_waitcnt vmcnt(3)
	s_nop 0
	v_pk_add_f32 v[4:5], v[34:35], v[12:13]
	v_pk_add_f32 v[2:3], v[32:33], v[10:11]
	global_store_dwordx4 v[40:41], v[2:5], off offset:512 sc1
	s_waitcnt vmcnt(3)
	s_nop 0
	v_pk_add_f32 v[4:5], v[38:39], v[16:17]
	v_pk_add_f32 v[2:3], v[36:37], v[14:15]
	global_store_dwordx4 v[40:41], v[2:5], off offset:576 sc1
	s_branch .LBB0_1445

; template <class Epi, class Pre>
; __device__ __forceinline__ void meta_gemm(const bf16_t* __restrict__ A, int lda, const bf16_t* __restrict__ Bt, int ldb, int N, int K, Epi& epi, Pre pre) {
;     ...
;     const bf16_t* ap = A + (size_t)(NREAL + fr) * lda + wid * ks + fq * 8;
;     const bf16_t* bp = Bt + (size_t)(cb + fr) * ldb + wid * ks + fq * 8;
; #pragma unroll 4
;     for (int k0 = 0; k0 < ks; k0 += 32) {
;       const bf16x8 a = *(const bf16x8*)(ap + k0);
; #pragma unroll
;       for (int bj = 0; bj < 2; ++bj)
; #pragma unroll
;         for (int n = 0; n < 2; ++n) { const bf16x8 b = *(const bf16x8*)(bp + (size_t)(bj * 128 + n * 16) * ldb + k0); acc[bj][n] = __builtin_amdgcn_mfma_f32_16x16x32_bf16(b, a, acc[bj][n], 0, 0, 0); }
;     }
; #pragma unroll
;     for (int bj = 0; bj < 2; ++bj)
; #pragma unroll
;       for (int n = 0; n < 2; ++n)
; #pragma unroll
;         for (int j = 0; j < 4; ++j) part[(wid * 16 + (bj * 2 + n) * 4 + j) * 64 + lane] = acc[bj][n][j];
;     __syncthreads();
;     if (wid < 4) {
;       f32x4 v[2][2];
; #pragma unroll
;       for (int bj = 0; bj < 2; ++bj)
; #pragma unroll
;         for (int n = 0; n < 2; ++n)
; #pragma unroll
;           for (int j = 0; j < 4; ++j) { float s = 0.f;
; #pragma unroll
;             for (int w = 0; w < 8; ++w) s += part[(w * 16 + (bj * 2 + n) * 4 + j) * 64 + lane];
.LBB0_1470:
	s_and_b32 s6, s1, 0x60
	s_and_b32 s7, s0, 0xffffff00
	s_or_b32 s8, s7, s6
	v_or_b32_e32 v18, s8, v0
	v_ashrrev_i32_e32 v19, 31, v18
	v_lshlrev_b64 v[18:19], 11, v[18:19]
	v_lshl_add_u64 v[44:45], v[34:35], 0, v[18:19]
	global_load_dwordx4 v[18:21], v[44:45], off
	global_load_dwordx4 v[40:43], v[44:45], off offset:64
	v_add_co_u32_e32 v46, vcc, 0x8000, v44
	v_addc_co_u32_e32 v47, vcc, 0, v45, vcc
	v_add_co_u32_e32 v48, vcc, 0x40000, v44
	v_addc_co_u32_e32 v49, vcc, 0, v45, vcc
	v_add_co_u32_e32 v50, vcc, 0x48000, v44
	v_addc_co_u32_e32 v51, vcc, 0, v45, vcc
	global_load_dwordx4 v[160:163], v[46:47], off
	global_load_dwordx4 v[168:171], v[46:47], off offset:64
	global_load_dwordx4 v[172:175], v[48:49], off
	global_load_dwordx4 v[176:179], v[48:49], off offset:64
	global_load_dwordx4 v[180:183], v[50:51], off
	global_load_dwordx4 v[184:187], v[50:51], off offset:64
	global_load_dwordx4 v[188:191], v[44:45], off offset:128
	global_load_dwordx4 v[192:195], v[46:47], off offset:128
	global_load_dwordx4 v[196:199], v[48:49], off offset:128
	global_load_dwordx4 v[200:203], v[50:51], off offset:128
	global_load_dwordx4 v[204:207], v[44:45], off offset:192
	global_load_dwordx4 v[220:223], v[46:47], off offset:192
	global_load_dwordx4 v[224:227], v[48:49], off offset:192
	global_load_dwordx4 v[248:251], v[50:51], off offset:192
	s_waitcnt vmcnt(15)
	v_mfma_f32_16x16x32_bf16 v[18:21], v[18:21], v[10:13], 0
	s_waitcnt vmcnt(14)
	v_mfma_f32_16x16x32_bf16 v[18:21], v[40:43], v[2:5], v[18:21]
	s_waitcnt vmcnt(13)
	v_mfma_f32_16x16x32_bf16 v[22:25], v[160:163], v[10:13], 0
	s_waitcnt vmcnt(12)
	v_mfma_f32_16x16x32_bf16 v[22:25], v[168:171], v[2:5], v[22:25]
	s_waitcnt vmcnt(11)
	v_mfma_f32_16x16x32_bf16 v[26:29], v[172:175], v[10:13], 0
	s_waitcnt vmcnt(10)
	v_mfma_f32_16x16x32_bf16 v[26:29], v[176:179], v[2:5], v[26:29]
	s_waitcnt vmcnt(9)
	v_mfma_f32_16x16x32_bf16 v[30:33], v[180:183], v[10:13], 0
	s_waitcnt vmcnt(8)
	v_mfma_f32_16x16x32_bf16 v[30:33], v[184:187], v[2:5], v[30:33]
	s_waitcnt vmcnt(7)
	v_mfma_f32_16x16x32_bf16 v[18:21], v[188:191], v[6:9], v[18:21]
	s_waitcnt vmcnt(6)
	v_mfma_f32_16x16x32_bf16 v[22:25], v[192:195], v[6:9], v[22:25]
	s_waitcnt vmcnt(5)
	v_mfma_f32_16x16x32_bf16 v[26:29], v[196:199], v[6:9], v[26:29]
	s_waitcnt vmcnt(4)
	v_mfma_f32_16x16x32_bf16 v[30:33], v[200:203], v[6:9], v[30:33]
	s_waitcnt vmcnt(3)
	v_mfma_f32_16x16x32_bf16 v[18:21], v[204:207], v[14:17], v[18:21]
	s_waitcnt vmcnt(2)
	v_mfma_f32_16x16x32_bf16 v[22:25], v[220:223], v[14:17], v[22:25]
	s_waitcnt vmcnt(1)
	v_mfma_f32_16x16x32_bf16 v[26:29], v[224:227], v[14:17], v[26:29]
	s_waitcnt vmcnt(0)
	v_mfma_f32_16x16x32_bf16 v[30:33], v[248:251], v[14:17], v[30:33]
	s_nop 3
	ds_write2st64_b32 v59, v18, v19 offset1:1
	ds_write2st64_b32 v59, v20, v21 offset0:2 offset1:3
	ds_write2st64_b32 v59, v22, v23 offset0:4 offset1:5
	ds_write2st64_b32 v59, v24, v25 offset0:6 offset1:7
	s_nop 0
	ds_write2st64_b32 v59, v26, v27 offset0:8 offset1:9
	ds_write2st64_b32 v59, v28, v29 offset0:10 offset1:11
	s_nop 0
	ds_write2st64_b32 v59, v30, v31 offset0:12 offset1:13
	ds_write2st64_b32 v59, v32, v33 offset0:14 offset1:15
	s_waitcnt lgkmcnt(0)
	s_barrier
	s_and_saveexec_b64 s[6:7], s[4:5]
	s_cbranch_execz .LBB0_1469
	ds_read2st64_b32 v[18:19], v58 offset1:1
	ds_read2st64_b32 v[20:21], v58 offset0:16 offset1:17
	ds_read2st64_b32 v[22:23], v58 offset0:32 offset1:33
	ds_read2st64_b32 v[24:25], v58 offset0:48 offset1:49
	ds_read2st64_b32 v[26:27], v58 offset0:64 offset1:65
	ds_read2st64_b32 v[28:29], v58 offset0:80 offset1:81
	ds_read2st64_b32 v[30:31], v58 offset0:96 offset1:97
	ds_read2st64_b32 v[32:33], v58 offset0:112 offset1:113
	ds_read2st64_b32 v[40:41], v58 offset0:2 offset1:3
	ds_read2st64_b32 v[42:43], v58 offset0:18 offset1:19
	ds_read2st64_b32 v[44:45], v58 offset0:34 offset1:35
	ds_read2st64_b32 v[46:47], v58 offset0:50 offset1:51
	ds_read2st64_b32 v[48:49], v58 offset0:66 offset1:67
	ds_read2st64_b32 v[50:51], v58 offset0:82 offset1:83
	ds_read2st64_b32 v[52:53], v58 offset0:98 offset1:99
	ds_read2st64_b32 v[54:55], v58 offset0:114 offset1:115
	s_waitcnt lgkmcnt(7)
	v_pk_add_f32 v[40:41], v[40:41], 0 op_sel_hi:[1,0]
	v_pk_add_f32 v[18:19], v[18:19], 0 op_sel_hi:[1,0]
	s_ashr_i32 s9, s8, 31
	v_pk_add_f32 v[18:19], v[18:19], v[20:21]
	s_waitcnt lgkmcnt(6)
	v_pk_add_f32 v[20:21], v[40:41], v[42:43]
	v_pk_add_f32 v[18:19], v[18:19], v[22:23]
	s_waitcnt lgkmcnt(5)
	v_pk_add_f32 v[20:21], v[20:21], v[44:45]
	v_pk_add_f32 v[18:19], v[18:19], v[24:25]
	s_waitcnt lgkmcnt(4)
	v_pk_add_f32 v[20:21], v[20:21], v[46:47]
	v_pk_add_f32 v[18:19], v[18:19], v[26:27]
	s_waitcnt lgkmcnt(3)
	v_pk_add_f32 v[20:21], v[20:21], v[48:49]
	v_pk_add_f32 v[18:19], v[18:19], v[28:29]
	s_waitcnt lgkmcnt(2)
	v_pk_add_f32 v[20:21], v[20:21], v[50:51]
	v_pk_add_f32 v[18:19], v[18:19], v[30:31]
	s_waitcnt lgkmcnt(1)
	v_pk_add_f32 v[20:21], v[20:21], v[52:53]
	v_pk_add_f32 v[40:41], v[18:19], v[32:33]
	s_waitcnt lgkmcnt(0)
	v_pk_add_f32 v[42:43], v[20:21], v[54:55]
	ds_read2st64_b32 v[18:19], v58 offset0:4 offset1:5
	ds_read2st64_b32 v[20:21], v58 offset0:20 offset1:21
	ds_read2st64_b32 v[22:23], v58 offset0:36 offset1:37
	ds_read2st64_b32 v[24:25], v58 offset0:52 offset1:53
	ds_read2st64_b32 v[26:27], v58 offset0:68 offset1:69
	ds_read2st64_b32 v[28:29], v58 offset0:84 offset1:85
	ds_read2st64_b32 v[30:31], v58 offset0:100 offset1:101
	ds_read2st64_b32 v[32:33], v58 offset0:116 offset1:117
	ds_read2st64_b32 v[44:45], v58 offset0:6 offset1:7
	ds_read2st64_b32 v[46:47], v58 offset0:22 offset1:23
	ds_read2st64_b32 v[48:49], v58 offset0:38 offset1:39
	ds_read2st64_b32 v[50:51], v58 offset0:54 offset1:55
	ds_read2st64_b32 v[52:53], v58 offset0:70 offset1:71
	ds_read2st64_b32 v[54:55], v58 offset0:86 offset1:87
	ds_read2st64_b32 v[56:57], v58 offset0:102 offset1:103
	ds_read2st64_b32 v[60:61], v58 offset0:118 offset1:119
	s_waitcnt lgkmcnt(7)
; template <class Epi, class Pre>
; __device__ __forceinline__ void meta_gemm(const bf16_t* __restrict__ A, int lda, const bf16_t* __restrict__ Bt, int ldb, int N, int K, Epi& epi, Pre pre) {
;     ...
;       for (int bj = 0; bj < 2; ++bj)
; #pragma unroll
;         for (int n = 0; n < 2; ++n)
; #pragma unroll
;           for (int j = 0; j < 4; ++j) { float s = 0.f;
; #pragma unroll
;             for (int w = 0; w < 8; ++w) s += part[(w * 16 + (bj * 2 + n) * 4 + j) * 64 + lane];
;             v[bj][n][j] = s; }
;       pre(fr, fq);
;       epi(NREAL + 16 * wid + fr, cb, fq, v[0][0], v[0][1], v[1][0], v[1][1]);
	v_pk_add_f32 v[44:45], v[44:45], 0 op_sel_hi:[1,0]
	v_pk_add_f32 v[18:19], v[18:19], 0 op_sel_hi:[1,0]
	s_lshl_b64 s[8:9], s[8:9], 2
	v_pk_add_f32 v[18:19], v[18:19], v[20:21]
	s_waitcnt lgkmcnt(6)
	v_pk_add_f32 v[20:21], v[44:45], v[46:47]
	v_pk_add_f32 v[18:19], v[18:19], v[22:23]
	s_waitcnt lgkmcnt(5)
	v_pk_add_f32 v[20:21], v[20:21], v[48:49]
	v_pk_add_f32 v[18:19], v[18:19], v[24:25]
	s_waitcnt lgkmcnt(4)
	v_pk_add_f32 v[20:21], v[20:21], v[50:51]
	v_pk_add_f32 v[18:19], v[18:19], v[26:27]
	s_waitcnt lgkmcnt(3)
	v_pk_add_f32 v[20:21], v[20:21], v[52:53]
	v_pk_add_f32 v[18:19], v[18:19], v[28:29]
	s_waitcnt lgkmcnt(2)
	v_pk_add_f32 v[20:21], v[20:21], v[54:55]
	v_pk_add_f32 v[18:19], v[18:19], v[30:31]
	s_waitcnt lgkmcnt(1)
	v_pk_add_f32 v[20:21], v[20:21], v[56:57]
	v_pk_add_f32 v[44:45], v[18:19], v[32:33]
	s_waitcnt lgkmcnt(0)
	v_pk_add_f32 v[46:47], v[20:21], v[60:61]
	ds_read2st64_b32 v[18:19], v58 offset0:8 offset1:9
	ds_read2st64_b32 v[20:21], v58 offset0:24 offset1:25
	ds_read2st64_b32 v[22:23], v58 offset0:40 offset1:41
	ds_read2st64_b32 v[24:25], v58 offset0:56 offset1:57
	ds_read2st64_b32 v[26:27], v58 offset0:72 offset1:73
	ds_read2st64_b32 v[28:29], v58 offset0:88 offset1:89
	ds_read2st64_b32 v[30:31], v58 offset0:104 offset1:105
	ds_read2st64_b32 v[32:33], v58 offset0:120 offset1:121
	ds_read2st64_b32 v[48:49], v58 offset0:10 offset1:11
	ds_read2st64_b32 v[50:51], v58 offset0:26 offset1:27
	ds_read2st64_b32 v[52:53], v58 offset0:42 offset1:43
	ds_read2st64_b32 v[54:55], v58 offset0:58 offset1:59
	ds_read2st64_b32 v[56:57], v58 offset0:74 offset1:75
	ds_read2st64_b32 v[60:61], v58 offset0:90 offset1:91
	ds_read2st64_b32 v[62:63], v58 offset0:106 offset1:107
	ds_read2st64_b32 v[64:65], v58 offset0:122 offset1:123
	s_waitcnt lgkmcnt(7)
	v_pk_add_f32 v[48:49], v[48:49], 0 op_sel_hi:[1,0]
	v_pk_add_f32 v[18:19], v[18:19], 0 op_sel_hi:[1,0]
	s_nop 0
	v_pk_add_f32 v[18:19], v[18:19], v[20:21]
	s_waitcnt lgkmcnt(6)
	v_pk_add_f32 v[20:21], v[48:49], v[50:51]
	v_pk_add_f32 v[18:19], v[18:19], v[22:23]
	s_waitcnt lgkmcnt(5)
	v_pk_add_f32 v[20:21], v[20:21], v[52:53]
	v_pk_add_f32 v[18:19], v[18:19], v[24:25]
	s_waitcnt lgkmcnt(4)
	v_pk_add_f32 v[20:21], v[20:21], v[54:55]
	v_pk_add_f32 v[18:19], v[18:19], v[26:27]
	s_waitcnt lgkmcnt(3)
	v_pk_add_f32 v[20:21], v[20:21], v[56:57]
	v_pk_add_f32 v[18:19], v[18:19], v[28:29]
	s_waitcnt lgkmcnt(2)
	v_pk_add_f32 v[20:21], v[20:21], v[60:61]
	v_pk_add_f32 v[18:19], v[18:19], v[30:31]
	s_waitcnt lgkmcnt(1)
	v_pk_add_f32 v[20:21], v[20:21], v[62:63]
	v_pk_add_f32 v[48:49], v[18:19], v[32:33]
	s_waitcnt lgkmcnt(0)
	v_pk_add_f32 v[50:51], v[20:21], v[64:65]
	ds_read2st64_b32 v[18:19], v58 offset0:12 offset1:13
	ds_read2st64_b32 v[20:21], v58 offset0:28 offset1:29
	ds_read2st64_b32 v[22:23], v58 offset0:44 offset1:45
	ds_read2st64_b32 v[24:25], v58 offset0:60 offset1:61
	ds_read2st64_b32 v[26:27], v58 offset0:76 offset1:77
	ds_read2st64_b32 v[28:29], v58 offset0:92 offset1:93
	ds_read2st64_b32 v[30:31], v58 offset0:108 offset1:109
	ds_read2st64_b32 v[32:33], v58 offset0:124 offset1:125
	ds_read2st64_b32 v[52:53], v58 offset0:14 offset1:15
	ds_read2st64_b32 v[54:55], v58 offset0:30 offset1:31
	ds_read2st64_b32 v[56:57], v58 offset0:46 offset1:47
	ds_read2st64_b32 v[60:61], v58 offset0:62 offset1:63
	ds_read2st64_b32 v[62:63], v58 offset0:78 offset1:79
	ds_read2st64_b32 v[64:65], v58 offset0:94 offset1:95
	ds_read2st64_b32 v[66:67], v58 offset0:110 offset1:111
	ds_read2st64_b32 v[68:69], v58 offset0:126 offset1:127
	s_waitcnt lgkmcnt(7)
	v_pk_add_f32 v[52:53], v[52:53], 0 op_sel_hi:[1,0]
	v_pk_add_f32 v[18:19], v[18:19], 0 op_sel_hi:[1,0]
	s_nop 0
	v_pk_add_f32 v[18:19], v[18:19], v[20:21]
	s_waitcnt lgkmcnt(6)
	v_pk_add_f32 v[20:21], v[52:53], v[54:55]
	v_pk_add_f32 v[18:19], v[18:19], v[22:23]
	s_waitcnt lgkmcnt(5)
	v_pk_add_f32 v[20:21], v[20:21], v[56:57]
	v_pk_add_f32 v[18:19], v[18:19], v[24:25]
	s_waitcnt lgkmcnt(4)
	v_pk_add_f32 v[20:21], v[20:21], v[60:61]
	v_pk_add_f32 v[18:19], v[18:19], v[26:27]
	s_waitcnt lgkmcnt(3)
	v_pk_add_f32 v[20:21], v[20:21], v[62:63]
	v_pk_add_f32 v[18:19], v[18:19], v[28:29]
	s_waitcnt lgkmcnt(2)
	v_pk_add_f32 v[20:21], v[20:21], v[64:65]
	v_pk_add_f32 v[18:19], v[18:19], v[30:31]
	s_waitcnt lgkmcnt(1)
	v_pk_add_f32 v[20:21], v[20:21], v[66:67]
	v_lshl_add_u64 v[30:31], v[38:39], 0, s[8:9]
	v_pk_add_f32 v[52:53], v[18:19], v[32:33]
	s_waitcnt lgkmcnt(0)
	v_pk_add_f32 v[54:55], v[20:21], v[68:69]
	global_load_dwordx4 v[18:21], v[30:31], off
	global_load_dwordx4 v[22:25], v[30:31], off offset:64
	global_load_dwordx4 v[26:29], v[30:31], off offset:512
	s_nop 0
	global_load_dwordx4 v[30:33], v[30:31], off offset:576
	v_lshl_add_u64 v[56:57], v[36:37], 0, s[8:9]
	s_waitcnt vmcnt(3)
	v_pk_add_f32 v[20:21], v[42:43], v[20:21]
	v_pk_add_f32 v[18:19], v[40:41], v[18:19]
	global_store_dwordx4 v[56:57], v[18:21], off sc1
	s_waitcnt vmcnt(3)
	s_nop 0
	v_pk_add_f32 v[20:21], v[46:47], v[24:25]
	v_pk_add_f32 v[18:19], v[44:45], v[22:23]
	global_store_dwordx4 v[56:57], v[18:21], off offset:64 sc1
	s_waitcnt vmcnt(3)
	s_nop 0
	v_pk_add_f32 v[20:21], v[50:51], v[28:29]
	v_pk_add_f32 v[18:19], v[48:49], v[26:27]
	global_store_dwordx4 v[56:57], v[18:21], off offset:512 sc1
	s_waitcnt vmcnt(3)
	s_nop 0
	v_pk_add_f32 v[20:21], v[54:55], v[32:33]
	v_pk_add_f32 v[18:19], v[52:53], v[30:31]
	global_store_dwordx4 v[56:57], v[18:21], off offset:576 sc1
	s_branch .LBB0_1469

; template <class Epi, class Pre>
; __device__ __forceinline__ void meta_gemm(const bf16_t* __restrict__ A, int lda, const bf16_t* __restrict__ Bt, int ldb, int N, int K, Epi& epi, Pre pre) {
;     ...
;     const bf16_t* ap = A + (size_t)(NREAL + fr) * lda + wid * ks + fq * 8;
;     const bf16_t* bp = Bt + (size_t)(cb + fr) * ldb + wid * ks + fq * 8;
; #pragma unroll 4
;     for (int k0 = 0; k0 < ks; k0 += 32) {
;       const bf16x8 a = *(const bf16x8*)(ap + k0);
; #pragma unroll
;       for (int bj = 0; bj < 2; ++bj)
; #pragma unroll
;         for (int n = 0; n < 2; ++n) { const bf16x8 b = *(const bf16x8*)(bp + (size_t)(bj * 128 + n * 16) * ldb + k0); acc[bj][n] = __builtin_amdgcn_mfma_f32_16x16x32_bf16(b, a, acc[bj][n], 0, 0, 0); }
;     }
; #pragma unroll
;     for (int bj = 0; bj < 2; ++bj)
; #pragma unroll
;       for (int n = 0; n < 2; ++n)
; #pragma unroll
;         for (int j = 0; j < 4; ++j) part[(wid * 16 + (bj * 2 + n) * 4 + j) * 64 + lane] = acc[bj][n][j];
;     __syncthreads();
;     if (wid < 4) {
;       f32x4 v[2][2];
; #pragma unroll
;       for (int bj = 0; bj < 2; ++bj)
; #pragma unroll
;         for (int n = 0; n < 2; ++n)
; #pragma unroll
;           for (int j = 0; j < 4; ++j) { float s = 0.f;
; #pragma unroll
;             for (int w = 0; w < 8; ++w) s += part[(w * 16 + (bj * 2 + n) * 4 + j) * 64 + lane];
.LBB0_1515:
	s_and_b32 s6, s1, 0xffffff00
	s_and_b32 s12, s10, 0x60
	v_or_b32_e32 v23, s6, v0
	v_or_b32_e32 v24, s12, v23
	v_ashrrev_i32_e32 v25, 31, v24
	v_lshlrev_b64 v[24:25], 11, v[24:25]
	v_lshl_add_u64 v[44:45], v[18:19], 0, v[24:25]
	global_load_dwordx4 v[24:27], v[44:45], off
	global_load_dwordx4 v[40:43], v[44:45], off offset:64
	v_add_co_u32_e32 v46, vcc, 0x8000, v44
	v_addc_co_u32_e32 v47, vcc, 0, v45, vcc
	v_add_co_u32_e32 v48, vcc, 0x40000, v44
	v_addc_co_u32_e32 v49, vcc, 0, v45, vcc
	v_add_co_u32_e32 v50, vcc, 0x48000, v44
	v_addc_co_u32_e32 v51, vcc, 0, v45, vcc
	global_load_dwordx4 v[160:163], v[46:47], off
	global_load_dwordx4 v[168:171], v[46:47], off offset:64
	global_load_dwordx4 v[172:175], v[48:49], off
	global_load_dwordx4 v[176:179], v[48:49], off offset:64
	global_load_dwordx4 v[180:183], v[50:51], off
	global_load_dwordx4 v[184:187], v[50:51], off offset:64
	global_load_dwordx4 v[188:191], v[44:45], off offset:128
	global_load_dwordx4 v[192:195], v[46:47], off offset:128
	global_load_dwordx4 v[196:199], v[48:49], off offset:128
	global_load_dwordx4 v[200:203], v[50:51], off offset:128
	global_load_dwordx4 v[204:207], v[44:45], off offset:192
	global_load_dwordx4 v[220:223], v[46:47], off offset:192
	global_load_dwordx4 v[224:227], v[48:49], off offset:192
	global_load_dwordx4 v[248:251], v[50:51], off offset:192
	s_waitcnt vmcnt(15)
	v_mfma_f32_16x16x32_bf16 v[24:27], v[24:27], v[10:13], 0
	s_waitcnt vmcnt(14)
	v_mfma_f32_16x16x32_bf16 v[24:27], v[40:43], v[2:5], v[24:27]
	s_waitcnt vmcnt(13)
	v_mfma_f32_16x16x32_bf16 v[28:31], v[160:163], v[10:13], 0
	s_waitcnt vmcnt(12)
	v_mfma_f32_16x16x32_bf16 v[28:31], v[168:171], v[2:5], v[28:31]
	s_waitcnt vmcnt(11)
	v_mfma_f32_16x16x32_bf16 v[32:35], v[172:175], v[10:13], 0
	s_waitcnt vmcnt(10)
	v_mfma_f32_16x16x32_bf16 v[32:35], v[176:179], v[2:5], v[32:35]
	s_waitcnt vmcnt(9)
	v_mfma_f32_16x16x32_bf16 v[36:39], v[180:183], v[10:13], 0
	s_waitcnt vmcnt(8)
	v_mfma_f32_16x16x32_bf16 v[36:39], v[184:187], v[2:5], v[36:39]
	s_waitcnt vmcnt(7)
	v_mfma_f32_16x16x32_bf16 v[24:27], v[188:191], v[6:9], v[24:27]
	s_waitcnt vmcnt(6)
	v_mfma_f32_16x16x32_bf16 v[28:31], v[192:195], v[6:9], v[28:31]
	s_waitcnt vmcnt(5)
	v_mfma_f32_16x16x32_bf16 v[32:35], v[196:199], v[6:9], v[32:35]
	s_waitcnt vmcnt(4)
	v_mfma_f32_16x16x32_bf16 v[36:39], v[200:203], v[6:9], v[36:39]
	s_waitcnt vmcnt(3)
	v_mfma_f32_16x16x32_bf16 v[24:27], v[204:207], v[14:17], v[24:27]
	s_waitcnt vmcnt(2)
	v_mfma_f32_16x16x32_bf16 v[28:31], v[220:223], v[14:17], v[28:31]
	s_waitcnt vmcnt(1)
	v_mfma_f32_16x16x32_bf16 v[32:35], v[224:227], v[14:17], v[32:35]
	s_waitcnt vmcnt(0)
	v_mfma_f32_16x16x32_bf16 v[36:39], v[248:251], v[14:17], v[36:39]
	s_nop 3
	ds_write2st64_b32 v75, v24, v25 offset1:1
	ds_write2st64_b32 v75, v26, v27 offset0:2 offset1:3
	ds_write2st64_b32 v75, v28, v29 offset0:4 offset1:5
	ds_write2st64_b32 v75, v30, v31 offset0:6 offset1:7
	s_nop 0
	ds_write2st64_b32 v75, v32, v33 offset0:8 offset1:9
	ds_write2st64_b32 v75, v34, v35 offset0:10 offset1:11
	s_nop 0
	ds_write2st64_b32 v75, v36, v37 offset0:12 offset1:13
	ds_write2st64_b32 v75, v38, v39 offset0:14 offset1:15
	s_waitcnt lgkmcnt(0)
	s_barrier
	s_and_saveexec_b64 s[6:7], s[4:5]
	s_cbranch_execz .LBB0_1514
	ds_read2st64_b32 v[76:77], v74 offset1:1
	ds_read2st64_b32 v[38:39], v74 offset0:2 offset1:3
	ds_read2st64_b32 v[72:73], v74 offset0:4 offset1:5
	ds_read2st64_b32 v[24:25], v74 offset0:6 offset1:7
	ds_read2st64_b32 v[78:79], v74 offset0:16 offset1:17
	ds_read2st64_b32 v[42:43], v74 offset0:18 offset1:19
	ds_read2st64_b32 v[80:81], v74 offset0:20 offset1:21
	ds_read2st64_b32 v[26:27], v74 offset0:22 offset1:23
	ds_read2st64_b32 v[82:83], v74 offset0:32 offset1:33
	ds_read2st64_b32 v[44:45], v74 offset0:34 offset1:35
	ds_read2st64_b32 v[84:85], v74 offset0:36 offset1:37
	ds_read2st64_b32 v[28:29], v74 offset0:38 offset1:39
	ds_read2st64_b32 v[86:87], v74 offset0:48 offset1:49
	ds_read2st64_b32 v[46:47], v74 offset0:50 offset1:51
	ds_read2st64_b32 v[88:89], v74 offset0:52 offset1:53
	ds_read2st64_b32 v[30:31], v74 offset0:54 offset1:55
	ds_read2st64_b32 v[90:91], v74 offset0:64 offset1:65
	ds_read2st64_b32 v[48:49], v74 offset0:66 offset1:67
	ds_read2st64_b32 v[92:93], v74 offset0:68 offset1:69
	ds_read2st64_b32 v[32:33], v74 offset0:70 offset1:71
	ds_read2st64_b32 v[94:95], v74 offset0:80 offset1:81
	ds_read2st64_b32 v[50:51], v74 offset0:82 offset1:83
	ds_read2st64_b32 v[96:97], v74 offset0:84 offset1:85
	ds_read2st64_b32 v[34:35], v74 offset0:86 offset1:87
	ds_read2st64_b32 v[98:99], v74 offset0:96 offset1:97
	ds_read2st64_b32 v[52:53], v74 offset0:98 offset1:99
	ds_read2st64_b32 v[100:101], v74 offset0:100 offset1:101
	ds_read2st64_b32 v[36:37], v74 offset0:102 offset1:103
	ds_read2st64_b32 v[102:103], v74 offset0:112 offset1:113
	ds_read2st64_b32 v[54:55], v74 offset0:114 offset1:115
	ds_read2st64_b32 v[104:105], v74 offset0:116 offset1:117
	ds_read2st64_b32 v[40:41], v74 offset0:118 offset1:119
	ds_read2st64_b32 v[106:107], v74 offset0:8 offset1:9
	ds_read2st64_b32 v[108:109], v74 offset0:10 offset1:11
	ds_read2st64_b32 v[110:111], v74 offset0:12 offset1:13
	ds_read2st64_b32 v[60:61], v74 offset0:14 offset1:15
	ds_read2st64_b32 v[112:113], v74 offset0:24 offset1:25
	ds_read2st64_b32 v[114:115], v74 offset0:26 offset1:27
	ds_read2st64_b32 v[116:117], v74 offset0:28 offset1:29
	ds_read2st64_b32 v[64:65], v74 offset0:30 offset1:31
	ds_read2st64_b32 v[118:119], v74 offset0:40 offset1:41
	ds_read2st64_b32 v[120:121], v74 offset0:42 offset1:43
	ds_read2st64_b32 v[122:123], v74 offset0:44 offset1:45
	ds_read2st64_b32 v[66:67], v74 offset0:46 offset1:47
	ds_read2st64_b32 v[124:125], v74 offset0:56 offset1:57
	ds_read2st64_b32 v[126:127], v74 offset0:58 offset1:59
	ds_read2st64_b32 v[128:129], v74 offset0:60 offset1:61
	ds_read2st64_b32 v[70:71], v74 offset0:62 offset1:63
	ds_read2st64_b32 v[130:131], v74 offset0:72 offset1:73
	ds_read2st64_b32 v[132:133], v74 offset0:74 offset1:75
	ds_read2st64_b32 v[134:135], v74 offset0:76 offset1:77
	ds_read2st64_b32 v[56:57], v74 offset0:78 offset1:79
	ds_read2st64_b32 v[136:137], v74 offset0:88 offset1:89
	ds_read2st64_b32 v[138:139], v74 offset0:90 offset1:91
	ds_read2st64_b32 v[140:141], v74 offset0:92 offset1:93
	ds_read2st64_b32 v[58:59], v74 offset0:94 offset1:95
	ds_read2st64_b32 v[142:143], v74 offset0:104 offset1:105
	ds_read2st64_b32 v[144:145], v74 offset0:106 offset1:107
	ds_read2st64_b32 v[146:147], v74 offset0:108 offset1:109
	ds_read2st64_b32 v[62:63], v74 offset0:110 offset1:111
	ds_read2st64_b32 v[148:149], v74 offset0:120 offset1:121
	ds_read2st64_b32 v[150:151], v74 offset0:122 offset1:123
	ds_read2st64_b32 v[152:153], v74 offset0:124 offset1:125
	ds_read2st64_b32 v[68:69], v74 offset0:126 offset1:127
	s_waitcnt lgkmcnt(14)
; __device__ __forceinline__ unsigned cvt_pk_bf16(float lo, float hi) { const f32x2 v = {lo, hi}; return __builtin_bit_cast(unsigned, __builtin_convertvector(v, bf16v2)); }
;   __device__ __forceinline__ void operator()(int row, int cb, int fq, f32x4 a, f32x4 b, f32x4 c, f32x4 d) const { group(row, cb, fq, a, b); group(row, cb + 128, fq, c, d); }
;   __device__ __forceinline__ void operator()(int row, int cb, int fq, f32x4 a, f32x4 b, f32x4 c, f32x4 d) const { group(row, cb, fq, a, b); group(row, cb + 128, fq, c, d); }
; __device__ __forceinline__ float silu_mul(float g, float u) { return g * __builtin_amdgcn_rcpf(1.0f + __builtin_amdgcn_exp2f(-g * LOG2E)) * u; }
;   __device__ __forceinline__ void operator()(int row, int cb, int fq, f32x4 g0, f32x4 g1, f32x4 u0, f32x4 u1) const {
;     bf16_t* p = act + (size_t)row * DFF + (cb >> 8) * 128 + (cb & 255) + fq * 8; f32x4 o0, o1;
; #pragma unroll
;     for (int j = 0; j < 4; ++j) { o0[j] = silu_mul(g0[j], u0[j]); o1[j] = silu_mul(g1[j], u1[j]); }
;     u32x4 w; w.x = cvt_pk_bf16(o0[0], o0[1]); w.y = cvt_pk_bf16(o0[2], o0[3]); w.z = cvt_pk_bf16(o1[0], o1[1]); w.w = cvt_pk_bf16(o1[2], o1[3]);
;     *(u32x4*)p = w;
;   }
; template <class Epi, class Pre>
; __device__ __forceinline__ void meta_gemm(const bf16_t* __restrict__ A, int lda, const bf16_t* __restrict__ Bt, int ldb, int N, int K, Epi& epi, Pre pre) {
;     ...
;           for (int j = 0; j < 4; ++j) { float s = 0.f;
; #pragma unroll
;             for (int w = 0; w < 8; ++w) s += part[(w * 16 + (bj * 2 + n) * 4 + j) * 64 + lane];
;             v[bj][n][j] = s; }
	v_pk_add_f32 v[76:77], v[76:77], 0 op_sel_hi:[1,0]
	v_pk_add_f32 v[72:73], v[72:73], 0 op_sel_hi:[1,0]
	v_pk_add_f32 v[76:77], v[76:77], v[78:79]
	v_pk_add_f32 v[72:73], v[72:73], v[80:81]
	v_pk_add_f32 v[76:77], v[76:77], v[82:83]
	v_pk_add_f32 v[72:73], v[72:73], v[84:85]
	v_pk_add_f32 v[76:77], v[76:77], v[86:87]
	v_pk_add_f32 v[72:73], v[72:73], v[88:89]
	v_pk_add_f32 v[76:77], v[76:77], v[90:91]
	v_pk_add_f32 v[72:73], v[72:73], v[92:93]
	v_pk_add_f32 v[76:77], v[76:77], v[94:95]
	v_pk_add_f32 v[72:73], v[72:73], v[96:97]
	v_pk_add_f32 v[76:77], v[76:77], v[98:99]
	v_pk_add_f32 v[72:73], v[72:73], v[100:101]
	v_pk_add_f32 v[76:77], v[76:77], v[102:103]
	v_pk_add_f32 v[72:73], v[72:73], v[104:105]
	v_mul_f32_e32 v23, 0xbfb8aa3b, v76
	v_exp_f32_e32 v23, v23
	v_mul_f32_e32 v82, 0xbfb8aa3b, v77
	v_exp_f32_e32 v83, v82
	v_pk_add_f32 v[38:39], v[38:39], 0 op_sel_hi:[1,0]
	v_add_f32_e32 v23, 1.0, v23
	v_rcp_f32_e32 v82, v23
	v_add_f32_e32 v23, 1.0, v83
	v_rcp_f32_e32 v83, v23
	v_mul_f32_e32 v23, 0xbfb8aa3b, v72
	v_pk_add_f32 v[38:39], v[38:39], v[42:43]
	v_exp_f32_e32 v23, v23
	v_mul_f32_e32 v80, 0xbfb8aa3b, v73
	v_pk_add_f32 v[38:39], v[38:39], v[44:45]
	v_exp_f32_e32 v81, v80
	v_pk_add_f32 v[38:39], v[38:39], v[46:47]
	v_add_f32_e32 v23, 1.0, v23
	v_pk_add_f32 v[38:39], v[38:39], v[48:49]
	v_rcp_f32_e32 v80, v23
	v_pk_add_f32 v[38:39], v[38:39], v[50:51]
	v_add_f32_e32 v23, 1.0, v81
	v_pk_add_f32 v[38:39], v[38:39], v[52:53]
	v_pk_add_f32 v[24:25], v[24:25], 0 op_sel_hi:[1,0]
	v_pk_add_f32 v[38:39], v[38:39], v[54:55]
	v_rcp_f32_e32 v81, v23
	v_mul_f32_e32 v23, 0xbfb8aa3b, v38
	v_pk_add_f32 v[24:25], v[24:25], v[26:27]
	v_exp_f32_e32 v23, v23
	v_mul_f32_e32 v44, 0xbfb8aa3b, v39
	v_pk_add_f32 v[24:25], v[24:25], v[28:29]
	v_exp_f32_e32 v45, v44
	v_pk_add_f32 v[24:25], v[24:25], v[30:31]
	v_pk_add_f32 v[78:79], v[106:107], 0 op_sel_hi:[1,0]
	v_pk_add_f32 v[24:25], v[24:25], v[32:33]
	v_pk_add_f32 v[78:79], v[78:79], v[112:113]
	v_pk_add_f32 v[24:25], v[24:25], v[34:35]
	v_add_f32_e32 v23, 1.0, v23
	v_pk_add_f32 v[24:25], v[24:25], v[36:37]
	v_pk_add_f32 v[78:79], v[78:79], v[118:119]
	v_rcp_f32_e32 v44, v23
	v_add_f32_e32 v23, 1.0, v45
	v_pk_add_f32 v[24:25], v[24:25], v[40:41]
	v_pk_add_f32 v[78:79], v[78:79], v[124:125]
	v_rcp_f32_e32 v45, v23
	v_mul_f32_e32 v23, 0xbfb8aa3b, v24
	v_pk_add_f32 v[78:79], v[78:79], v[130:131]
	v_exp_f32_e32 v23, v23
	v_mul_f32_e32 v28, 0xbfb8aa3b, v25
	s_waitcnt lgkmcnt(11)
	v_pk_add_f32 v[78:79], v[78:79], v[136:137]
	v_exp_f32_e32 v29, v28
	s_waitcnt lgkmcnt(7)
	v_pk_add_f32 v[78:79], v[78:79], v[142:143]
	v_pk_mul_f32 v[76:77], v[76:77], v[82:83]
	s_waitcnt lgkmcnt(3)
	v_pk_add_f32 v[78:79], v[78:79], v[148:149]
	v_pk_add_f32 v[26:27], v[60:61], 0 op_sel_hi:[1,0]
	v_pk_mul_f32 v[76:77], v[76:77], v[78:79]
	v_pk_add_f32 v[78:79], v[110:111], 0 op_sel_hi:[1,0]
	v_pk_add_f32 v[42:43], v[108:109], 0 op_sel_hi:[1,0]
	v_pk_add_f32 v[26:27], v[26:27], v[64:65]
	v_add_f32_e32 v23, 1.0, v23
	v_pk_add_f32 v[78:79], v[78:79], v[116:117]
	v_pk_add_f32 v[42:43], v[42:43], v[114:115]
	v_pk_add_f32 v[26:27], v[26:27], v[66:67]
	v_rcp_f32_e32 v28, v23
	v_add_f32_e32 v23, 1.0, v29
	v_pk_add_f32 v[78:79], v[78:79], v[122:123]
	v_pk_add_f32 v[42:43], v[42:43], v[120:121]
	v_pk_add_f32 v[26:27], v[26:27], v[70:71]
	v_rcp_f32_e32 v29, v23
	v_pk_add_f32 v[78:79], v[78:79], v[128:129]
	v_pk_add_f32 v[42:43], v[42:43], v[126:127]
	v_pk_add_f32 v[26:27], v[26:27], v[56:57]
	v_pk_add_f32 v[78:79], v[78:79], v[134:135]
	v_pk_add_f32 v[42:43], v[42:43], v[132:133]
	v_pk_add_f32 v[26:27], v[26:27], v[58:59]
	v_pk_add_f32 v[78:79], v[78:79], v[140:141]
	v_pk_add_f32 v[42:43], v[42:43], v[138:139]
	v_pk_add_f32 v[26:27], v[26:27], v[62:63]
	s_and_b32 s14, s10, 0xffffff80
	v_pk_add_f32 v[78:79], v[78:79], v[146:147]
	v_pk_add_f32 v[42:43], v[42:43], v[144:145]
	s_waitcnt lgkmcnt(0)
	v_pk_add_f32 v[26:27], v[26:27], v[68:69]
	v_pk_mul_f32 v[24:25], v[24:25], v[28:29]
	s_ashr_i32 s15, s14, 31
	v_pk_add_f32 v[78:79], v[78:79], v[152:153]
	v_pk_mul_f32 v[72:73], v[72:73], v[80:81]
	v_pk_add_f32 v[42:43], v[42:43], v[150:151]
	v_pk_mul_f32 v[38:39], v[38:39], v[44:45]
	v_pk_mul_f32 v[28:29], v[24:25], v[26:27]
	v_lshl_add_u64 v[24:25], s[14:15], 1, v[20:21]
	s_lshl_b32 s90, s12, 1
	v_pk_mul_f32 v[72:73], v[72:73], v[78:79]
	v_pk_mul_f32 v[38:39], v[38:39], v[42:43]
	v_lshl_add_u64 v[24:25], v[24:25], 0, s[90:91]
	v_mov_b32_e32 v23, v1
	v_lshl_add_u64 v[30:31], v[24:25], 0, v[22:23]
	v_cvt_pk_bf16_f32 v24, v76, v77
	v_cvt_pk_bf16_f32 v25, v38, v39
	v_cvt_pk_bf16_f32 v26, v72, v73
	v_cvt_pk_bf16_f32 v27, v28, v29
	global_store_dwordx4 v[30:31], v[24:27], off sc1
	s_branch .LBB0_1514

; template <class Epi, class Pre>
; __device__ __forceinline__ void meta_gemm(const bf16_t* __restrict__ A, int lda, const bf16_t* __restrict__ Bt, int ldb, int N, int K, Epi& epi, Pre pre) {
;     ...
;     const bf16_t* ap = A + (size_t)(NREAL + fr) * lda + wid * ks + fq * 8;
;     const bf16_t* bp = Bt + (size_t)(cb + fr) * ldb + wid * ks + fq * 8;
; #pragma unroll 4
;     for (int k0 = 0; k0 < ks; k0 += 32) {
;       const bf16x8 a = *(const bf16x8*)(ap + k0);
; #pragma unroll
;       for (int bj = 0; bj < 2; ++bj)
; #pragma unroll
;         for (int n = 0; n < 2; ++n) { const bf16x8 b = *(const bf16x8*)(bp + (size_t)(bj * 128 + n * 16) * ldb + k0); acc[bj][n] = __builtin_amdgcn_mfma_f32_16x16x32_bf16(b, a, acc[bj][n], 0, 0, 0); }
;     }
.LBB0_1547:
	s_and_b32 s4, s10, 0x60
	s_and_b32 s5, s1, 0xffffff00
	s_or_b32 s4, s5, s4
	v_or_b32_e32 v2, s4, v0
	s_movk_i32 s5, 0x1600
	v_mad_i64_i32 v[34:35], s[8:9], v2, s5, v[24:25]
	v_add_co_u32_e32 v32, vcc, 0x16000, v34
	s_mov_b32 s5, 0xb0000
	s_nop 0
	v_addc_co_u32_e32 v33, vcc, 0, v35, vcc
	v_add_co_u32_e32 v30, vcc, s5, v34
	global_load_dwordx4 v[2:5], v[22:23], off
	global_load_dwordx4 v[6:9], v[34:35], off
	v_addc_co_u32_e32 v31, vcc, 0, v35, vcc
	v_add_co_u32_e32 v28, vcc, 0xc6000, v34
	global_load_dwordx4 v[10:13], v[32:33], off
	s_nop 0
	v_addc_co_u32_e32 v29, vcc, 0, v35, vcc
	global_load_dwordx4 v[14:17], v[30:31], off
	global_load_dwordx4 v[18:21], v[28:29], off
	global_load_dwordx4 v[54:57], v[22:23], off offset:64
	global_load_dwordx4 v[58:61], v[34:35], off offset:64
	global_load_dwordx4 v[62:65], v[32:33], off offset:64
	global_load_dwordx4 v[66:69], v[30:31], off offset:64
	global_load_dwordx4 v[70:73], v[28:29], off offset:64
	global_load_dwordx4 v[74:77], v[22:23], off offset:128
	global_load_dwordx4 v[78:81], v[34:35], off offset:128
	global_load_dwordx4 v[82:85], v[32:33], off offset:128
	global_load_dwordx4 v[86:89], v[30:31], off offset:128
	global_load_dwordx4 v[90:93], v[28:29], off offset:128
	global_load_dwordx4 v[94:97], v[22:23], off offset:192
	global_load_dwordx4 v[98:101], v[34:35], off offset:192
	global_load_dwordx4 v[102:105], v[32:33], off offset:192
	global_load_dwordx4 v[106:109], v[30:31], off offset:192
	global_load_dwordx4 v[110:113], v[28:29], off offset:192
	global_load_dwordx4 v[114:117], v[22:23], off offset:256
	global_load_dwordx4 v[118:121], v[34:35], off offset:256
	global_load_dwordx4 v[122:125], v[32:33], off offset:256
	global_load_dwordx4 v[126:129], v[30:31], off offset:256
	global_load_dwordx4 v[130:133], v[28:29], off offset:256
	global_load_dwordx4 v[134:137], v[22:23], off offset:320
	global_load_dwordx4 v[138:141], v[34:35], off offset:320
	global_load_dwordx4 v[142:145], v[32:33], off offset:320
	global_load_dwordx4 v[146:149], v[30:31], off offset:320
	global_load_dwordx4 v[150:153], v[28:29], off offset:320
	global_load_dwordx4 v[160:163], v[22:23], off offset:384
	global_load_dwordx4 v[168:171], v[34:35], off offset:384
	global_load_dwordx4 v[172:175], v[32:33], off offset:384
	global_load_dwordx4 v[176:179], v[30:31], off offset:384
	global_load_dwordx4 v[180:183], v[28:29], off offset:384
	s_waitcnt vmcnt(33)
	v_mfma_f32_16x16x32_bf16 v[6:9], v[6:9], v[2:5], 0
	s_waitcnt vmcnt(32)
	v_mfma_f32_16x16x32_bf16 v[10:13], v[10:13], v[2:5], 0
	s_waitcnt vmcnt(31)
	v_mfma_f32_16x16x32_bf16 v[14:17], v[14:17], v[2:5], 0
	s_waitcnt vmcnt(30)
	v_mfma_f32_16x16x32_bf16 v[2:5], v[18:21], v[2:5], 0
	s_waitcnt vmcnt(28)
	v_mfma_f32_16x16x32_bf16 v[6:9], v[58:61], v[54:57], v[6:9]
	s_waitcnt vmcnt(27)
	v_mfma_f32_16x16x32_bf16 v[10:13], v[62:65], v[54:57], v[10:13]
	s_waitcnt vmcnt(26)
	v_mfma_f32_16x16x32_bf16 v[14:17], v[66:69], v[54:57], v[14:17]
	s_waitcnt vmcnt(25)
	v_mfma_f32_16x16x32_bf16 v[2:5], v[70:73], v[54:57], v[2:5]
	s_waitcnt vmcnt(23)
	v_mfma_f32_16x16x32_bf16 v[6:9], v[78:81], v[74:77], v[6:9]
	s_waitcnt vmcnt(22)
	v_mfma_f32_16x16x32_bf16 v[10:13], v[82:85], v[74:77], v[10:13]
	s_waitcnt vmcnt(21)
	v_mfma_f32_16x16x32_bf16 v[14:17], v[86:89], v[74:77], v[14:17]
	s_waitcnt vmcnt(20)
	v_mfma_f32_16x16x32_bf16 v[2:5], v[90:93], v[74:77], v[2:5]
	s_waitcnt vmcnt(18)
	v_mfma_f32_16x16x32_bf16 v[6:9], v[98:101], v[94:97], v[6:9]
	s_waitcnt vmcnt(17)
	v_mfma_f32_16x16x32_bf16 v[10:13], v[102:105], v[94:97], v[10:13]
	s_waitcnt vmcnt(16)
	v_mfma_f32_16x16x32_bf16 v[14:17], v[106:109], v[94:97], v[14:17]
	s_waitcnt vmcnt(15)
	v_mfma_f32_16x16x32_bf16 v[2:5], v[110:113], v[94:97], v[2:5]
	s_nop 1
	global_load_dwordx4 v[54:57], v[22:23], off offset:448
	global_load_dwordx4 v[58:61], v[34:35], off offset:448
	global_load_dwordx4 v[62:65], v[32:33], off offset:448
	global_load_dwordx4 v[66:69], v[30:31], off offset:448
	global_load_dwordx4 v[70:73], v[28:29], off offset:448
	global_load_dwordx4 v[74:77], v[22:23], off offset:512
	global_load_dwordx4 v[78:81], v[34:35], off offset:512
	global_load_dwordx4 v[82:85], v[32:33], off offset:512
	global_load_dwordx4 v[86:89], v[30:31], off offset:512
	global_load_dwordx4 v[90:93], v[28:29], off offset:512
	global_load_dwordx4 v[94:97], v[22:23], off offset:576
	global_load_dwordx4 v[98:101], v[34:35], off offset:576
	global_load_dwordx4 v[102:105], v[32:33], off offset:576
	global_load_dwordx4 v[106:109], v[30:31], off offset:576
	global_load_dwordx4 v[110:113], v[28:29], off offset:576
	s_waitcnt vmcnt(28)
	v_mfma_f32_16x16x32_bf16 v[6:9], v[118:121], v[114:117], v[6:9]
	s_waitcnt vmcnt(27)
	v_mfma_f32_16x16x32_bf16 v[10:13], v[122:125], v[114:117], v[10:13]
	s_waitcnt vmcnt(26)
	v_mfma_f32_16x16x32_bf16 v[14:17], v[126:129], v[114:117], v[14:17]
	s_waitcnt vmcnt(25)
	v_mfma_f32_16x16x32_bf16 v[2:5], v[130:133], v[114:117], v[2:5]
	s_waitcnt vmcnt(23)
	v_mfma_f32_16x16x32_bf16 v[6:9], v[138:141], v[134:137], v[6:9]
	s_waitcnt vmcnt(22)
	v_mfma_f32_16x16x32_bf16 v[10:13], v[142:145], v[134:137], v[10:13]
	s_waitcnt vmcnt(21)
	v_mfma_f32_16x16x32_bf16 v[14:17], v[146:149], v[134:137], v[14:17]
	s_waitcnt vmcnt(20)
	v_mfma_f32_16x16x32_bf16 v[2:5], v[150:153], v[134:137], v[2:5]
	s_waitcnt vmcnt(18)
	v_mfma_f32_16x16x32_bf16 v[6:9], v[168:171], v[160:163], v[6:9]
	s_waitcnt vmcnt(17)
	v_mfma_f32_16x16x32_bf16 v[10:13], v[172:175], v[160:163], v[10:13]
	s_waitcnt vmcnt(16)
	v_mfma_f32_16x16x32_bf16 v[14:17], v[176:179], v[160:163], v[14:17]
	s_waitcnt vmcnt(15)
; template <class Epi, class Pre>
; __device__ __forceinline__ void meta_gemm(const bf16_t* __restrict__ A, int lda, const bf16_t* __restrict__ Bt, int ldb, int N, int K, Epi& epi, Pre pre) {
;     ...
;         for (int n = 0; n < 2; ++n) { const bf16x8 b = *(const bf16x8*)(bp + (size_t)(bj * 128 + n * 16) * ldb + k0); acc[bj][n] = __builtin_amdgcn_mfma_f32_16x16x32_bf16(b, a, acc[bj][n], 0, 0, 0); }
;     }
; #pragma unroll
;     for (int bj = 0; bj < 2; ++bj)
; #pragma unroll
;       for (int n = 0; n < 2; ++n)
; #pragma unroll
;         for (int j = 0; j < 4; ++j) part[(wid * 16 + (bj * 2 + n) * 4 + j) * 64 + lane] = acc[bj][n][j];
;     __syncthreads();
;     if (wid < 4) {
;       f32x4 v[2][2];
; #pragma unroll
;       for (int bj = 0; bj < 2; ++bj)
; #pragma unroll
;         for (int n = 0; n < 2; ++n)
; #pragma unroll
;           for (int j = 0; j < 4; ++j) { float s = 0.f;
; #pragma unroll
;             for (int w = 0; w < 8; ++w) s += part[(w * 16 + (bj * 2 + n) * 4 + j) * 64 + lane];
	v_mfma_f32_16x16x32_bf16 v[2:5], v[180:183], v[160:163], v[2:5]
	s_nop 1
	global_load_dwordx4 v[114:117], v[22:23], off offset:640
	global_load_dwordx4 v[118:121], v[34:35], off offset:640
	global_load_dwordx4 v[122:125], v[32:33], off offset:640
	global_load_dwordx4 v[126:129], v[30:31], off offset:640
	global_load_dwordx4 v[130:133], v[28:29], off offset:640
	s_waitcnt vmcnt(18)
	v_mfma_f32_16x16x32_bf16 v[6:9], v[58:61], v[54:57], v[6:9]
	s_waitcnt vmcnt(17)
	v_mfma_f32_16x16x32_bf16 v[10:13], v[62:65], v[54:57], v[10:13]
	s_waitcnt vmcnt(16)
	v_mfma_f32_16x16x32_bf16 v[14:17], v[66:69], v[54:57], v[14:17]
	s_waitcnt vmcnt(15)
	v_mfma_f32_16x16x32_bf16 v[2:5], v[70:73], v[54:57], v[2:5]
	s_waitcnt vmcnt(13)
	v_mfma_f32_16x16x32_bf16 v[6:9], v[78:81], v[74:77], v[6:9]
	s_waitcnt vmcnt(12)
	v_mfma_f32_16x16x32_bf16 v[36:39], v[82:85], v[74:77], v[10:13]
	s_waitcnt vmcnt(11)
	v_mfma_f32_16x16x32_bf16 v[44:47], v[86:89], v[74:77], v[14:17]
	s_waitcnt vmcnt(10)
	v_mfma_f32_16x16x32_bf16 v[2:5], v[90:93], v[74:77], v[2:5]
	s_waitcnt vmcnt(8)
	v_mfma_f32_16x16x32_bf16 v[10:13], v[98:101], v[94:97], v[6:9]
	s_waitcnt vmcnt(7)
	v_mfma_f32_16x16x32_bf16 v[14:17], v[102:105], v[94:97], v[36:39]
	s_waitcnt vmcnt(6)
	v_mfma_f32_16x16x32_bf16 v[6:9], v[106:109], v[94:97], v[44:47]
	s_waitcnt vmcnt(5)
	v_mfma_f32_16x16x32_bf16 v[2:5], v[110:113], v[94:97], v[2:5]
	s_waitcnt vmcnt(3)
	v_mfma_f32_16x16x32_bf16 v[10:13], v[118:121], v[114:117], v[10:13]
	s_waitcnt vmcnt(2)
	v_mfma_f32_16x16x32_bf16 v[14:17], v[122:125], v[114:117], v[14:17]
	s_waitcnt vmcnt(1)
	v_mfma_f32_16x16x32_bf16 v[6:9], v[126:129], v[114:117], v[6:9]
	s_waitcnt vmcnt(0)
	v_mfma_f32_16x16x32_bf16 v[2:5], v[130:133], v[114:117], v[2:5]
	s_nop 3
	ds_write2st64_b32 v43, v10, v11 offset1:1
	ds_write2st64_b32 v43, v12, v13 offset0:2 offset1:3
	ds_write2st64_b32 v43, v14, v15 offset0:4 offset1:5
	ds_write2st64_b32 v43, v16, v17 offset0:6 offset1:7
	s_nop 0
	ds_write2st64_b32 v43, v6, v7 offset0:8 offset1:9
	ds_write2st64_b32 v43, v8, v9 offset0:10 offset1:11
	s_nop 0
	ds_write2st64_b32 v43, v2, v3 offset0:12 offset1:13
	ds_write2st64_b32 v43, v4, v5 offset0:14 offset1:15
	s_waitcnt lgkmcnt(0)
	s_barrier
	s_and_saveexec_b64 s[8:9], s[2:3]
	s_cbranch_execz .LBB0_1546
	ds_read2st64_b32 v[2:3], v42 offset1:1
	ds_read2st64_b32 v[4:5], v42 offset0:16 offset1:17
	ds_read2st64_b32 v[6:7], v42 offset0:32 offset1:33
	ds_read2st64_b32 v[8:9], v42 offset0:48 offset1:49
	ds_read2st64_b32 v[10:11], v42 offset0:64 offset1:65
	ds_read2st64_b32 v[12:13], v42 offset0:80 offset1:81
	ds_read2st64_b32 v[14:15], v42 offset0:96 offset1:97
	ds_read2st64_b32 v[16:17], v42 offset0:112 offset1:113
	ds_read2st64_b32 v[18:19], v42 offset0:2 offset1:3
	ds_read2st64_b32 v[20:21], v42 offset0:18 offset1:19
	ds_read2st64_b32 v[28:29], v42 offset0:34 offset1:35
	ds_read2st64_b32 v[30:31], v42 offset0:50 offset1:51
	ds_read2st64_b32 v[32:33], v42 offset0:66 offset1:67
	ds_read2st64_b32 v[34:35], v42 offset0:82 offset1:83
	ds_read2st64_b32 v[36:37], v42 offset0:98 offset1:99
	ds_read2st64_b32 v[38:39], v42 offset0:114 offset1:115
	s_waitcnt lgkmcnt(7)
	v_pk_add_f32 v[18:19], v[18:19], 0 op_sel_hi:[1,0]
	v_pk_add_f32 v[2:3], v[2:3], 0 op_sel_hi:[1,0]
	s_ashr_i32 s5, s4, 31
	v_pk_add_f32 v[2:3], v[2:3], v[4:5]
	s_waitcnt lgkmcnt(6)
	v_pk_add_f32 v[4:5], v[18:19], v[20:21]
	v_pk_add_f32 v[2:3], v[2:3], v[6:7]
	s_waitcnt lgkmcnt(5)
	v_pk_add_f32 v[4:5], v[4:5], v[28:29]
	v_pk_add_f32 v[2:3], v[2:3], v[8:9]
	s_waitcnt lgkmcnt(4)
	v_pk_add_f32 v[4:5], v[4:5], v[30:31]
	v_pk_add_f32 v[2:3], v[2:3], v[10:11]
	s_waitcnt lgkmcnt(3)
	v_pk_add_f32 v[4:5], v[4:5], v[32:33]
	v_pk_add_f32 v[2:3], v[2:3], v[12:13]
	s_waitcnt lgkmcnt(2)
	v_pk_add_f32 v[4:5], v[4:5], v[34:35]
	v_pk_add_f32 v[2:3], v[2:3], v[14:15]
	s_waitcnt lgkmcnt(1)
	v_pk_add_f32 v[4:5], v[4:5], v[36:37]
	v_pk_add_f32 v[18:19], v[2:3], v[16:17]
	s_waitcnt lgkmcnt(0)
	v_pk_add_f32 v[20:21], v[4:5], v[38:39]
	ds_read2st64_b32 v[2:3], v42 offset0:4 offset1:5
	ds_read2st64_b32 v[4:5], v42 offset0:20 offset1:21
	ds_read2st64_b32 v[6:7], v42 offset0:36 offset1:37
	ds_read2st64_b32 v[8:9], v42 offset0:52 offset1:53
	ds_read2st64_b32 v[10:11], v42 offset0:68 offset1:69
	ds_read2st64_b32 v[12:13], v42 offset0:84 offset1:85
	ds_read2st64_b32 v[14:15], v42 offset0:100 offset1:101
	ds_read2st64_b32 v[16:17], v42 offset0:116 offset1:117
	ds_read2st64_b32 v[28:29], v42 offset0:6 offset1:7
	ds_read2st64_b32 v[30:31], v42 offset0:22 offset1:23
	ds_read2st64_b32 v[32:33], v42 offset0:38 offset1:39
	ds_read2st64_b32 v[34:35], v42 offset0:54 offset1:55
	ds_read2st64_b32 v[36:37], v42 offset0:70 offset1:71
	ds_read2st64_b32 v[38:39], v42 offset0:86 offset1:87
	ds_read2st64_b32 v[40:41], v42 offset0:102 offset1:103
	ds_read2st64_b32 v[44:45], v42 offset0:118 offset1:119
	s_waitcnt lgkmcnt(7)
	v_pk_add_f32 v[28:29], v[28:29], 0 op_sel_hi:[1,0]
	v_pk_add_f32 v[2:3], v[2:3], 0 op_sel_hi:[1,0]
	s_nop 0
	v_pk_add_f32 v[2:3], v[2:3], v[4:5]
	s_waitcnt lgkmcnt(6)
; template <class Epi, class Pre>
; __device__ __forceinline__ void meta_gemm(const bf16_t* __restrict__ A, int lda, const bf16_t* __restrict__ Bt, int ldb, int N, int K, Epi& epi, Pre pre) {
;     ...
;       for (int bj = 0; bj < 2; ++bj)
; #pragma unroll
;         for (int n = 0; n < 2; ++n)
; #pragma unroll
;           for (int j = 0; j < 4; ++j) { float s = 0.f;
; #pragma unroll
;             for (int w = 0; w < 8; ++w) s += part[(w * 16 + (bj * 2 + n) * 4 + j) * 64 + lane];
;             v[bj][n][j] = s; }
;       pre(fr, fq);
;       epi(NREAL + 16 * wid + fr, cb, fq, v[0][0], v[0][1], v[1][0], v[1][1]);
	v_pk_add_f32 v[4:5], v[28:29], v[30:31]
	v_pk_add_f32 v[2:3], v[2:3], v[6:7]
	s_waitcnt lgkmcnt(5)
	v_pk_add_f32 v[4:5], v[4:5], v[32:33]
	v_pk_add_f32 v[2:3], v[2:3], v[8:9]
	s_waitcnt lgkmcnt(4)
	v_pk_add_f32 v[4:5], v[4:5], v[34:35]
	v_pk_add_f32 v[2:3], v[2:3], v[10:11]
	s_waitcnt lgkmcnt(3)
	v_pk_add_f32 v[4:5], v[4:5], v[36:37]
	v_pk_add_f32 v[2:3], v[2:3], v[12:13]
	s_waitcnt lgkmcnt(2)
	v_pk_add_f32 v[4:5], v[4:5], v[38:39]
	v_pk_add_f32 v[2:3], v[2:3], v[14:15]
	s_waitcnt lgkmcnt(1)
	v_pk_add_f32 v[4:5], v[4:5], v[40:41]
	v_pk_add_f32 v[28:29], v[2:3], v[16:17]
	s_waitcnt lgkmcnt(0)
	v_pk_add_f32 v[30:31], v[4:5], v[44:45]
	ds_read2st64_b32 v[2:3], v42 offset0:8 offset1:9
	ds_read2st64_b32 v[4:5], v42 offset0:24 offset1:25
	ds_read2st64_b32 v[6:7], v42 offset0:40 offset1:41
	ds_read2st64_b32 v[8:9], v42 offset0:56 offset1:57
	ds_read2st64_b32 v[10:11], v42 offset0:72 offset1:73
	ds_read2st64_b32 v[12:13], v42 offset0:88 offset1:89
	ds_read2st64_b32 v[14:15], v42 offset0:104 offset1:105
	ds_read2st64_b32 v[16:17], v42 offset0:120 offset1:121
	ds_read2st64_b32 v[32:33], v42 offset0:10 offset1:11
	ds_read2st64_b32 v[34:35], v42 offset0:26 offset1:27
	ds_read2st64_b32 v[36:37], v42 offset0:42 offset1:43
	ds_read2st64_b32 v[38:39], v42 offset0:58 offset1:59
	ds_read2st64_b32 v[40:41], v42 offset0:74 offset1:75
	ds_read2st64_b32 v[44:45], v42 offset0:90 offset1:91
	ds_read2st64_b32 v[46:47], v42 offset0:106 offset1:107
	ds_read2st64_b32 v[48:49], v42 offset0:122 offset1:123
	s_waitcnt lgkmcnt(7)
	v_pk_add_f32 v[32:33], v[32:33], 0 op_sel_hi:[1,0]
	v_pk_add_f32 v[2:3], v[2:3], 0 op_sel_hi:[1,0]
	s_nop 0
	v_pk_add_f32 v[2:3], v[2:3], v[4:5]
	s_waitcnt lgkmcnt(6)
	v_pk_add_f32 v[4:5], v[32:33], v[34:35]
	v_pk_add_f32 v[2:3], v[2:3], v[6:7]
	s_waitcnt lgkmcnt(5)
	v_pk_add_f32 v[4:5], v[4:5], v[36:37]
	v_pk_add_f32 v[2:3], v[2:3], v[8:9]
	s_waitcnt lgkmcnt(4)
	v_pk_add_f32 v[4:5], v[4:5], v[38:39]
	v_pk_add_f32 v[2:3], v[2:3], v[10:11]
	s_waitcnt lgkmcnt(3)
	v_pk_add_f32 v[4:5], v[4:5], v[40:41]
	v_pk_add_f32 v[2:3], v[2:3], v[12:13]
	s_waitcnt lgkmcnt(2)
	v_pk_add_f32 v[4:5], v[4:5], v[44:45]
	v_pk_add_f32 v[2:3], v[2:3], v[14:15]
	s_waitcnt lgkmcnt(1)
	v_pk_add_f32 v[4:5], v[4:5], v[46:47]
	v_pk_add_f32 v[32:33], v[2:3], v[16:17]
	s_waitcnt lgkmcnt(0)
	v_pk_add_f32 v[34:35], v[4:5], v[48:49]
	ds_read2st64_b32 v[2:3], v42 offset0:12 offset1:13
	ds_read2st64_b32 v[4:5], v42 offset0:28 offset1:29
	ds_read2st64_b32 v[6:7], v42 offset0:44 offset1:45
	ds_read2st64_b32 v[8:9], v42 offset0:60 offset1:61
	ds_read2st64_b32 v[10:11], v42 offset0:76 offset1:77
	ds_read2st64_b32 v[12:13], v42 offset0:92 offset1:93
	ds_read2st64_b32 v[14:15], v42 offset0:108 offset1:109
	ds_read2st64_b32 v[16:17], v42 offset0:124 offset1:125
	ds_read2st64_b32 v[36:37], v42 offset0:14 offset1:15
	ds_read2st64_b32 v[38:39], v42 offset0:30 offset1:31
	ds_read2st64_b32 v[40:41], v42 offset0:46 offset1:47
	ds_read2st64_b32 v[44:45], v42 offset0:62 offset1:63
	ds_read2st64_b32 v[46:47], v42 offset0:78 offset1:79
	ds_read2st64_b32 v[48:49], v42 offset0:94 offset1:95
	ds_read2st64_b32 v[50:51], v42 offset0:110 offset1:111
	ds_read2st64_b32 v[52:53], v42 offset0:126 offset1:127
	s_waitcnt lgkmcnt(7)
	v_pk_add_f32 v[36:37], v[36:37], 0 op_sel_hi:[1,0]
	v_pk_add_f32 v[2:3], v[2:3], 0 op_sel_hi:[1,0]
	s_nop 0
	v_pk_add_f32 v[2:3], v[2:3], v[4:5]
	s_waitcnt lgkmcnt(6)
	v_pk_add_f32 v[4:5], v[36:37], v[38:39]
	v_pk_add_f32 v[2:3], v[2:3], v[6:7]
	s_waitcnt lgkmcnt(5)
	v_pk_add_f32 v[4:5], v[4:5], v[40:41]
	v_pk_add_f32 v[2:3], v[2:3], v[8:9]
	s_waitcnt lgkmcnt(4)
	v_pk_add_f32 v[4:5], v[4:5], v[44:45]
	v_pk_add_f32 v[2:3], v[2:3], v[10:11]
	s_waitcnt lgkmcnt(3)
	v_pk_add_f32 v[4:5], v[4:5], v[46:47]
	v_pk_add_f32 v[2:3], v[2:3], v[12:13]
	s_waitcnt lgkmcnt(2)
	v_pk_add_f32 v[4:5], v[4:5], v[48:49]
	v_pk_add_f32 v[2:3], v[2:3], v[14:15]
	s_waitcnt lgkmcnt(1)
	v_pk_add_f32 v[4:5], v[4:5], v[50:51]
	v_lshl_add_u64 v[40:41], s[4:5], 2, v[26:27]
	v_pk_add_f32 v[36:37], v[2:3], v[16:17]
	s_waitcnt lgkmcnt(0)
	v_pk_add_f32 v[38:39], v[4:5], v[52:53]
	global_load_dwordx4 v[2:5], v[40:41], off
	global_load_dwordx4 v[6:9], v[40:41], off offset:64
	global_load_dwordx4 v[10:13], v[40:41], off offset:512
	global_load_dwordx4 v[14:17], v[40:41], off offset:576
	s_waitcnt vmcnt(3)
	v_pk_add_f32 v[4:5], v[20:21], v[4:5]
	v_pk_add_f32 v[2:3], v[18:19], v[2:3]
	global_store_dwordx4 v[40:41], v[2:5], off sc1
	s_waitcnt vmcnt(3)
	s_nop 0
	v_pk_add_f32 v[4:5], v[30:31], v[8:9]
	v_pk_add_f32 v[2:3], v[28:29], v[6:7]
	global_store_dwordx4 v[40:41], v[2:5], off offset:64 sc1
	s_waitcnt vmcnt(3)
	s_nop 0
	v_pk_add_f32 v[4:5], v[34:35], v[12:13]
	v_pk_add_f32 v[2:3], v[32:33], v[10:11]
	global_store_dwordx4 v[40:41], v[2:5], off offset:512 sc1
	s_waitcnt vmcnt(3)
	s_nop 0
	v_pk_add_f32 v[4:5], v[38:39], v[16:17]
	v_pk_add_f32 v[2:3], v[36:37], v[14:15]
	global_store_dwordx4 v[40:41], v[2:5], off offset:576 sc1
	s_branch .LBB0_1546
